# scan phase: S5 chunk-carry scan items moved to blocks 256..399 (blocks 0..255 carry the long HGRN sequences), 512-block grid only
# speedup vs baseline: 1.0056x; 1.0039x over previous
.LBB0_1074:
	s_or_b64 exec, exec, s[4:5]
	ds_read_b64 v[10:11], v229 offset:63760
	s_waitcnt lgkmcnt(0)
	ds_read_b64 v[12:13], v229 offset:63760
	ds_read_b64 v[0:1], v229 offset:63760
	s_mov_b32 s0, 0x9000
	s_cmp_eq_u32 s77, 0x800
	s_cbranch_scc0 .Ls5rel_gen
	v_add_u32_e32 v5, 0xffff0000, v5
	v_cmp_gt_u32_e32 vcc, s0, v5
	s_branch .Ls5rel_go
.Ls5rel_gen:
	v_cmp_gt_i32_e32 vcc, s0, v5
.Ls5rel_go:
	s_and_saveexec_b64 s[4:5], vcc
	s_cbranch_execz .LBB0_1083
	s_mov_b64 s[0:1], 0x2a4c000
	s_waitcnt lgkmcnt(0)
	v_lshl_add_u64 v[6:7], v[0:1], 0, s[0:1]
	ds_read_b128 v[0:3], v229 offset:63504
	ds_read_b64 v[8:9], v229 offset:63752
	v_readlane_b32 s0, v255, 9
	v_lshlrev_b32_e32 v228, 3, v4
	s_lshl_b32 s10, s0, 5
	s_lshl_b32 s11, s0, 1
	v_lshl_add_u64 v[10:11], v[10:11], 0, v[228:229]
	s_mov_b64 s[0:1], 0xe754000
	v_lshl_add_u64 v[10:11], v[10:11], 0, s[0:1]
	v_lshl_add_u64 v[12:13], v[12:13], 0, v[228:229]
	s_mov_b64 s[0:1], 0xeb54000
	v_lshlrev_b32_e32 v52, 1, v4
	v_lshl_add_u64 v[12:13], v[12:13], 0, s[0:1]
	s_mov_b64 s[6:7], 0
	s_branch .LBB0_1077
